# stack12 + mix phase: sixth-round (sample-row) items dealt to waves 0-2 of every workgroup instead of all waves of workgroups 0-79
# speedup vs baseline: 1.0037x; 1.0026x over previous
; __device__ __forceinline__ void phase_mix(Frame& F, int l) {
;     ...
;     for (int it = gw; it < NITEM; it += NGW) {
;         const int tb = it / 5, c5 = it - tb * 5, ch = (c5 < 2) ? c5 : c5 + 4, m0 = tb * 8;
.LBB0_338:
	s_add_i32 s0, s0, s44
	s_cmpk_lt_i32 s0, 0x2800
	s_cbranch_scc1 .LBB0_339
	s_cmpk_lt_i32 s0, 0x3000
	s_cbranch_scc0 .LBB0_445
	s_sub_i32 s98, s0, 0x2800
	s_and_b32 s99, s98, 7
	s_lshl_b32 s99, s99, 8
	s_lshr_b32 s98, s98, 3
	s_add_i32 s98, s98, s99
	s_add_i32 s0, s98, 0x2800
	s_cmpk_lt_i32 s0, 0x2a80
	s_cbranch_scc0 .LBB0_445
